# conv main sweep loops: B-fragment base loop-carried, dead index update and two stale s_nop removed
# speedup vs baseline: 1.0077x; 1.0013x over previous
; template <int NQ, int NB, int L>
; __device__ __forceinline__ void conv_unit(LAS unsigned char* lds, const Args& a, int j, int seq0, int c, int tid) {
;     ...
;         const int dl_a = mw + 3 * GS - S_HI, dl_b = mw - S_LO;
;         static_assert(((3 * GS / 32) % 2 == 0) && (((S_HI - S_LO - 3 * GS) / 32 + 1) % 2 == 1), "conv step-count parity");
; #pragma unroll 1
;         for (int dl = d_lo; dl < dl_a; dl += 64) { CONV_STEP(Bc, Bn, dl, true); CONV_STEP(Bn, Bc, dl + 32, true); }
; #pragma unroll 1
;         for (int dl = dl_a; dl < dl_b; dl += 64) { CONV_STEP(Bc, Bn, dl, false); CONV_STEP(Bn, Bc, dl + 32, false); }
;         CONV_STEP(Bc, Bn, dl_b, false);
; #pragma unroll 1
;         for (int dl = dl_b + 32; dl <= d_hi; dl += 64) { CONV_STEP(Bn, Bc, dl, true); CONV_STEP(Bc, Bn, dl + 32, true); }
.LBB0_1340:
	v_mov_b32_e32 v114, 0
	v_mov_b32_e32 v32, v199
	v_add_u32_e32 v205, v199, v194
	v_add_u32_e32 v205, 0x16ffe, v205
	v_add_u32_e32 v206, v134, v194
	s_mov_b32 s94, s91
	v_mov_b32_e32 v115, v114
	v_mov_b32_e32 v116, v114
	v_mov_b32_e32 v117, v114
	v_mov_b32_e32 v118, v114
	v_mov_b32_e32 v119, v114
	v_mov_b32_e32 v120, v114
	v_mov_b32_e32 v121, v114
	v_mov_b32_e32 v122, v114
	v_mov_b32_e32 v123, v114
	v_mov_b32_e32 v124, v114
	v_mov_b32_e32 v125, v114
	v_mov_b32_e32 v126, v114
	v_mov_b32_e32 v127, v114
	v_mov_b32_e32 v128, v114
	v_mov_b32_e32 v129, v114
.LBB0_1341:
	s_waitcnt lgkmcnt(3)
	v_mfma_f32_16x16x32_bf16 v[60:63], v[70:73], v[82:85], v[90:93]
	s_mov_b32 s56, s71
	v_mfma_f32_16x16x32_bf16 v[64:67], v[74:77], v[82:85], v[86:89]
	s_waitcnt lgkmcnt(1)
	v_mfma_f32_16x16x32_bf16 v[34:37], v[78:81], v[24:27], v[36:39]
	v_mfma_f32_16x16x32_bf16 v[52:55], v[16:19], v[82:85], v[52:55]
	v_mfma_f32_16x16x32_bf16 v[56:59], v[78:81], v[82:85], v[94:97]
	v_mfma_f32_16x16x32_bf16 v[40:43], v[16:19], v[106:109], v[40:43]
	v_mfma_f32_16x16x32_bf16 v[28:31], v[78:81], v[106:109], v[28:31]
	v_mfma_f32_16x16x32_bf16 v[44:47], v[70:73], v[106:109], v[44:47]
	v_mfma_f32_16x16x32_bf16 v[48:51], v[74:77], v[106:109], v[48:51]
	ds_read_b128 v[82:85], v206 offset:8576
	ds_read_b128 v[106:109], v206 offset:8832
	ds_read_b128 v[130:133], v206 offset:9088
	ds_read_b128 v[148:151], v206 offset:9344
	v_mfma_f32_16x16x32_bf16 v[20:23], v[16:19], v[24:27], v[20:23]
	v_mfma_f32_16x16x32_bf16 v[102:105], v[70:73], v[24:27], v[102:105]
	v_mfma_f32_16x16x32_bf16 v[98:101], v[74:77], v[24:27], v[98:101]
	s_waitcnt lgkmcnt(4)
	v_mfma_f32_16x16x32_bf16 v[24:27], v[16:19], v[110:113], v[114:117]
	ds_read2_b32 v[16:17], v205 offset0:24 offset1:25
	ds_read2_b32 v[68:69], v205 offset0:25 offset1:26
	ds_read2_b32 v[18:19], v205 offset0:27 offset1:28
	ds_read2_b32 v[86:87], v205 offset0:16 offset1:17
	ds_read2_b32 v[88:89], v205 offset0:17 offset1:18
	ds_read2_b32 v[90:91], v205 offset0:19 offset1:20
	v_mfma_f32_16x16x32_bf16 v[78:81], v[78:81], v[110:113], v[118:121]
	v_mfma_f32_16x16x32_bf16 v[122:125], v[70:73], v[110:113], v[122:125]
	v_mfma_f32_16x16x32_bf16 v[126:129], v[74:77], v[110:113], v[126:129]
	s_waitcnt lgkmcnt(3)
	v_alignbit_b32 v19, v19, v18, v15
	v_alignbit_b32 v18, v18, v69, v14
	v_alignbit_b32 v17, v69, v17, v13
	v_alignbit_b32 v16, v68, v16, v12
	v_mfma_f32_16x16x32_bf16 v[118:121], v[74:77], v[148:151], v[78:81]
	s_waitcnt lgkmcnt(0)
	s_nop 1
	v_alignbit_b32 v81, v91, v90, v15
	v_alignbit_b32 v80, v90, v89, v14
	v_alignbit_b32 v79, v89, v87, v13
	v_alignbit_b32 v78, v88, v86, v12
	v_mfma_f32_16x16x32_bf16 v[94:97], v[74:77], v[82:85], v[56:59]
	v_mfma_f32_16x16x32_bf16 v[36:39], v[74:77], v[130:133], v[34:37]
	v_mfma_f32_16x16x32_bf16 v[90:93], v[16:19], v[82:85], v[60:63]
	v_mfma_f32_16x16x32_bf16 v[86:89], v[78:81], v[82:85], v[64:67]
	v_mfma_f32_16x16x32_bf16 v[52:55], v[70:73], v[82:85], v[52:55]
	ds_read_b128 v[82:85], v206 offset:8512
	v_mfma_f32_16x16x32_bf16 v[40:43], v[70:73], v[106:109], v[40:43]
	v_mfma_f32_16x16x32_bf16 v[28:31], v[74:77], v[106:109], v[28:31]
	v_mfma_f32_16x16x32_bf16 v[114:117], v[70:73], v[148:151], v[24:27]
	v_mfma_f32_16x16x32_bf16 v[44:47], v[16:19], v[106:109], v[44:47]
	v_mfma_f32_16x16x32_bf16 v[48:51], v[78:81], v[106:109], v[48:51]
	ds_read_b128 v[106:109], v206 offset:8768
	ds_read_b128 v[24:27], v206 offset:9024
	ds_read_b128 v[110:113], v206 offset:9280
	ds_read2_b32 v[34:35], v205 offset0:8 offset1:9
	ds_read2_b32 v[56:57], v205 offset0:9 offset1:10
	ds_read2_b32 v[58:59], v205 offset0:11 offset1:12
	ds_read2_b32 v[60:61], v205 offset0:0 offset1:1
	ds_read2_b32 v[62:63], v205 offset0:1 offset1:2
	ds_read2_b32 v[64:65], v205 offset0:3 offset1:4
	v_mfma_f32_16x16x32_bf16 v[20:23], v[70:73], v[130:133], v[20:23]
	s_waitcnt lgkmcnt(4)
	v_alignbit_b32 v71, v57, v35, v13
	s_waitcnt lgkmcnt(3)
	v_alignbit_b32 v73, v59, v58, v15
	v_mfma_f32_16x16x32_bf16 v[102:105], v[16:19], v[130:133], v[102:105]
	v_alignbit_b32 v72, v58, v57, v14
	v_alignbit_b32 v70, v56, v34, v12
	v_mfma_f32_16x16x32_bf16 v[98:101], v[78:81], v[130:133], v[98:101]
	v_mfma_f32_16x16x32_bf16 v[122:125], v[16:19], v[148:151], v[122:125]
	v_mfma_f32_16x16x32_bf16 v[126:129], v[78:81], v[148:151], v[126:129]
	s_add_i32 s94, s94, 64
	s_addk_i32 s71, 0xff80
	s_waitcnt lgkmcnt(0)
	v_alignbit_b32 v77, v65, v64, v15
	v_alignbit_b32 v76, v64, v63, v14
	v_alignbit_b32 v75, v63, v61, v13
	v_alignbit_b32 v74, v62, v60, v12
	v_add_u32_e32 v206, 0xffffff80, v206
	s_cmp_gt_i32 s94, s50
	v_add_u32_e32 v205, 0xffffff80, v205
	s_cbranch_scc0 .LBB0_1341
	v_sub_u32_e32 v134, v206, v194
	v_mfma_f32_16x16x32_bf16 v[66:69], v[16:19], v[82:85], v[52:55]
	v_add_u32_e32 v32, s75, v193
	v_mfma_f32_16x16x32_bf16 v[54:57], v[70:73], v[106:109], v[44:47]
	v_mfma_f32_16x16x32_bf16 v[50:53], v[74:77], v[106:109], v[48:51]
	v_mfma_f32_16x16x32_bf16 v[46:49], v[16:19], v[24:27], v[20:23]
	s_nop 2
	v_add_u32_e32 v20, v134, v194
	v_add_u32_e32 v21, s83, v193
	v_mfma_f32_16x16x32_bf16 v[62:65], v[16:19], v[106:109], v[40:43]
	v_mfma_f32_16x16x32_bf16 v[58:61], v[78:81], v[106:109], v[28:31]
	v_mfma_f32_16x16x32_bf16 v[42:45], v[78:81], v[24:27], v[36:39]
	v_mfma_f32_16x16x32_bf16 v[34:37], v[70:73], v[24:27], v[102:105]
	v_mfma_f32_16x16x32_bf16 v[24:27], v[74:77], v[24:27], v[98:101]
	ds_read_b128 v[130:133], v20 offset:8832
	s_nop 1
	ds_read_b128 v[98:101], v20 offset:9088
	v_mfma_f32_16x16x32_bf16 v[38:41], v[16:19], v[110:113], v[114:117]
	ds_read2_b32 v[16:17], v21 offset0:1 offset1:2
	ds_read2_b32 v[18:19], v21 offset0:3 offset1:4
	ds_read2_b32 v[106:107], v32 offset1:1
	ds_read2_b32 v[102:103], v21 offset1:1
	ds_read_b128 v[114:117], v20 offset:9344
	s_waitcnt lgkmcnt(3)
	v_alignbit_b32 v105, v19, v18, v15
	v_mfma_f32_16x16x32_bf16 v[28:31], v[78:81], v[110:113], v[118:121]
	s_nop 2
	ds_read2_b32 v[118:119], v32 offset0:1 offset1:2
	ds_read2_b32 v[108:109], v32 offset0:3 offset1:4
	v_alignbit_b32 v104, v18, v17, v14
	s_waitcnt lgkmcnt(3)
	v_alignbit_b32 v103, v17, v103, v13
	v_mfma_f32_16x16x32_bf16 v[20:23], v[70:73], v[110:113], v[122:125]
	v_alignbit_b32 v102, v16, v102, v12
	v_mfma_f32_16x16x32_bf16 v[16:19], v[74:77], v[110:113], v[126:129]
	s_waitcnt lgkmcnt(0)
	v_alignbit_b32 v109, v109, v108, v15
	v_alignbit_b32 v108, v108, v119, v14
	v_alignbit_b32 v107, v119, v107, v13
	v_alignbit_b32 v106, v118, v106, v12
	v_mov_b64_e32 v[112:113], v[72:73]
	v_mov_b64_e32 v[120:121], v[76:77]
	s_movk_i32 s71, 0xc0
	v_mov_b32_e32 v32, v216
	s_mov_b32 s94, s92
	v_mov_b64_e32 v[110:111], v[70:71]
	v_mov_b64_e32 v[118:119], v[74:75]
	s_branch .LBB0_1344

; template <int NQ, int NB, int L>
; __device__ __forceinline__ void conv_unit(LAS unsigned char* lds, const Args& a, int j, int seq0, int c, int tid) {
;     ...
;         const int dl_a = mw + 3 * GS - S_HI, dl_b = mw - S_LO;
;         static_assert(((3 * GS / 32) % 2 == 0) && (((S_HI - S_LO - 3 * GS) / 32 + 1) % 2 == 1), "conv step-count parity");
; #pragma unroll 1
;         for (int dl = d_lo; dl < dl_a; dl += 64) { CONV_STEP(Bc, Bn, dl, true); CONV_STEP(Bn, Bc, dl + 32, true); }
; #pragma unroll 1
;         for (int dl = dl_a; dl < dl_b; dl += 64) { CONV_STEP(Bc, Bn, dl, false); CONV_STEP(Bn, Bc, dl + 32, false); }
;         CONV_STEP(Bc, Bn, dl_b, false);
; #pragma unroll 1
;         for (int dl = dl_b + 32; dl <= d_hi; dl += 64) { CONV_STEP(Bn, Bc, dl, true); CONV_STEP(Bc, Bn, dl + 32, true); }
.LBB0_1545:
	v_mov_b32_e32 v122, 0
	v_mov_b32_e32 v32, v222
	v_add_u32_e32 v205, v222, v217
	v_add_u32_e32 v205, 0x1acfe, v205
	v_add_u32_e32 v206, v142, v217
	s_mov_b32 vcc_lo, s86
	v_mov_b32_e32 v123, v122
	v_mov_b32_e32 v124, v122
	v_mov_b32_e32 v125, v122
	v_mov_b32_e32 v126, v122
	v_mov_b32_e32 v127, v122
	v_mov_b32_e32 v128, v122
	v_mov_b32_e32 v129, v122
	v_mov_b32_e32 v130, v122
	v_mov_b32_e32 v131, v122
	v_mov_b32_e32 v132, v122
	v_mov_b32_e32 v133, v122
	v_mov_b32_e32 v134, v122
	v_mov_b32_e32 v135, v122
	v_mov_b32_e32 v136, v122
	v_mov_b32_e32 v137, v122
.LBB0_1546:
	s_waitcnt lgkmcnt(3)
	v_mfma_f32_16x16x32_bf16 v[68:71], v[78:81], v[90:93], v[94:97]
	s_waitcnt lgkmcnt(1)
	v_mfma_f32_16x16x32_bf16 v[28:31], v[24:27], v[36:39], v[28:31]
	v_mfma_f32_16x16x32_bf16 v[44:47], v[86:89], v[36:39], v[44:47]
	s_mov_b32 s49, s56
	v_mfma_f32_16x16x32_bf16 v[110:113], v[78:81], v[36:39], v[110:113]
	v_mfma_f32_16x16x32_bf16 v[106:109], v[82:85], v[36:39], v[106:109]
	v_mfma_f32_16x16x32_bf16 v[60:63], v[24:27], v[90:93], v[60:63]
	v_mfma_f32_16x16x32_bf16 v[64:67], v[86:89], v[90:93], v[102:105]
	v_mfma_f32_16x16x32_bf16 v[72:75], v[82:85], v[90:93], v[98:101]
	v_mfma_f32_16x16x32_bf16 v[48:51], v[24:27], v[114:117], v[48:51]
	v_mfma_f32_16x16x32_bf16 v[40:43], v[86:89], v[114:117], v[40:43]
	v_mfma_f32_16x16x32_bf16 v[52:55], v[78:81], v[114:117], v[52:55]
	v_mfma_f32_16x16x32_bf16 v[56:59], v[82:85], v[114:117], v[56:59]
	ds_read_b128 v[90:93], v206 offset:16768
	ds_read_b128 v[114:117], v206 offset:17280
	ds_read_b128 v[138:141], v206 offset:17792
	ds_read_b128 v[178:181], v206 offset:18304
	s_waitcnt lgkmcnt(4)
	v_mfma_f32_16x16x32_bf16 v[34:37], v[24:27], v[118:121], v[122:125]
	ds_read2_b32 v[24:25], v205 offset0:24 offset1:25
	ds_read2_b32 v[38:39], v205 offset0:25 offset1:26
	ds_read2_b32 v[26:27], v205 offset0:27 offset1:28
	ds_read2_b32 v[76:77], v205 offset0:16 offset1:17
	ds_read2_b32 v[98:99], v205 offset0:17 offset1:18
	ds_read2_b32 v[94:95], v205 offset0:19 offset1:20
	v_mfma_f32_16x16x32_bf16 v[86:89], v[86:89], v[118:121], v[126:129]
	v_mfma_f32_16x16x32_bf16 v[130:133], v[78:81], v[118:121], v[130:133]
	v_mfma_f32_16x16x32_bf16 v[134:137], v[82:85], v[118:121], v[134:137]
	s_waitcnt lgkmcnt(3)
	v_alignbit_b32 v27, v27, v26, v23
	v_alignbit_b32 v26, v26, v39, v22
	v_alignbit_b32 v25, v39, v25, v21
	v_alignbit_b32 v24, v38, v24, v20
	v_mfma_f32_16x16x32_bf16 v[126:129], v[82:85], v[178:181], v[86:89]
	s_waitcnt lgkmcnt(0)
	s_nop 1
	v_alignbit_b32 v89, v95, v94, v23
	v_alignbit_b32 v88, v94, v99, v22
	v_alignbit_b32 v87, v99, v77, v21
	v_alignbit_b32 v86, v98, v76, v20
	v_mfma_f32_16x16x32_bf16 v[102:105], v[82:85], v[90:93], v[64:67]
	v_mfma_f32_16x16x32_bf16 v[122:125], v[78:81], v[178:181], v[34:37]
	v_mfma_f32_16x16x32_bf16 v[94:97], v[24:27], v[90:93], v[68:71]
	v_mfma_f32_16x16x32_bf16 v[98:101], v[86:89], v[90:93], v[72:75]
	v_mfma_f32_16x16x32_bf16 v[60:63], v[78:81], v[90:93], v[60:63]
	ds_read_b128 v[90:93], v206 offset:16704
	v_mfma_f32_16x16x32_bf16 v[48:51], v[78:81], v[114:117], v[48:51]
	v_mfma_f32_16x16x32_bf16 v[40:43], v[82:85], v[114:117], v[40:43]
	v_mfma_f32_16x16x32_bf16 v[52:55], v[24:27], v[114:117], v[52:55]
	v_mfma_f32_16x16x32_bf16 v[56:59], v[86:89], v[114:117], v[56:59]
	ds_read_b128 v[114:117], v206 offset:17216
	ds_read_b128 v[36:39], v206 offset:17728
	ds_read_b128 v[118:121], v206 offset:18240
	ds_read2_b32 v[34:35], v205 offset0:8 offset1:9
	ds_read2_b32 v[64:65], v205 offset0:9 offset1:10
	ds_read2_b32 v[66:67], v205 offset0:11 offset1:12
	ds_read2_b32 v[68:69], v205 offset0:0 offset1:1
	ds_read2_b32 v[70:71], v205 offset0:1 offset1:2
	ds_read2_b32 v[72:73], v205 offset0:3 offset1:4
	v_mfma_f32_16x16x32_bf16 v[28:31], v[78:81], v[138:141], v[28:31]
	s_waitcnt lgkmcnt(4)
	v_alignbit_b32 v79, v65, v35, v21
	s_waitcnt lgkmcnt(3)
	v_alignbit_b32 v81, v67, v66, v23
	v_mfma_f32_16x16x32_bf16 v[44:47], v[82:85], v[138:141], v[44:47]
	v_alignbit_b32 v80, v66, v65, v22
	v_alignbit_b32 v78, v64, v34, v20
	v_mfma_f32_16x16x32_bf16 v[110:113], v[24:27], v[138:141], v[110:113]
	v_mfma_f32_16x16x32_bf16 v[106:109], v[86:89], v[138:141], v[106:109]
	v_mfma_f32_16x16x32_bf16 v[130:133], v[24:27], v[178:181], v[130:133]
	v_mfma_f32_16x16x32_bf16 v[134:137], v[86:89], v[178:181], v[134:137]
	s_add_i32 vcc_lo, vcc_lo, 64
	s_addk_i32 s56, 0xff80
	s_waitcnt lgkmcnt(0)
	v_alignbit_b32 v85, v73, v72, v23
	v_alignbit_b32 v84, v72, v71, v22
	v_alignbit_b32 v83, v71, v69, v21
	v_alignbit_b32 v82, v70, v68, v20
	v_add_u32_e32 v206, 0xffffff80, v206
	s_cmp_ge_i32 vcc_lo, s51
	v_add_u32_e32 v205, 0xffffff80, v205
	s_cbranch_scc0 .LBB0_1546
	v_sub_u32_e32 v142, v206, v217
	v_mfma_f32_16x16x32_bf16 v[74:77], v[24:27], v[90:93], v[60:63]
	v_add_u32_e32 v32, s97, v216
	v_mfma_f32_16x16x32_bf16 v[62:65], v[78:81], v[114:117], v[52:55]
	v_mfma_f32_16x16x32_bf16 v[58:61], v[82:85], v[114:117], v[56:59]
	v_mfma_f32_16x16x32_bf16 v[54:57], v[24:27], v[36:39], v[28:31]
	s_nop 2
	v_add_u32_e32 v28, v142, v217
	v_add_u32_e32 v29, s50, v216
	v_mfma_f32_16x16x32_bf16 v[70:73], v[24:27], v[114:117], v[48:51]
	v_mfma_f32_16x16x32_bf16 v[66:69], v[86:89], v[114:117], v[40:43]
	v_mfma_f32_16x16x32_bf16 v[50:53], v[86:89], v[36:39], v[44:47]
	v_mfma_f32_16x16x32_bf16 v[42:45], v[78:81], v[36:39], v[110:113]
	v_mfma_f32_16x16x32_bf16 v[34:37], v[82:85], v[36:39], v[106:109]
	ds_read_b128 v[138:141], v28 offset:17280
	s_nop 1
	ds_read_b128 v[106:109], v28 offset:17792
	v_mfma_f32_16x16x32_bf16 v[46:49], v[24:27], v[118:121], v[122:125]
	ds_read2_b32 v[24:25], v29 offset0:1 offset1:2
	ds_read2_b32 v[26:27], v29 offset0:3 offset1:4
	ds_read2_b32 v[114:115], v32 offset1:1
	ds_read2_b32 v[110:111], v29 offset1:1
	ds_read_b128 v[122:125], v28 offset:18304
	s_waitcnt lgkmcnt(3)
	v_alignbit_b32 v113, v27, v26, v23
	v_mfma_f32_16x16x32_bf16 v[38:41], v[86:89], v[118:121], v[126:129]
	s_nop 2
	ds_read2_b32 v[126:127], v32 offset0:1 offset1:2
	ds_read2_b32 v[116:117], v32 offset0:3 offset1:4
	v_alignbit_b32 v112, v26, v25, v22
	s_waitcnt lgkmcnt(3)
	v_alignbit_b32 v111, v25, v111, v21
	v_mfma_f32_16x16x32_bf16 v[28:31], v[78:81], v[118:121], v[130:133]
	v_alignbit_b32 v110, v24, v110, v20
	v_mfma_f32_16x16x32_bf16 v[24:27], v[82:85], v[118:121], v[134:137]
	s_waitcnt lgkmcnt(0)
	v_alignbit_b32 v117, v117, v116, v23
	v_alignbit_b32 v116, v116, v127, v22
	v_alignbit_b32 v115, v127, v115, v21
	v_alignbit_b32 v114, v126, v114, v20
	v_mov_b64_e32 v[120:121], v[80:81]
	v_mov_b64_e32 v[128:129], v[84:85]
	s_movk_i32 s56, 0x1c0
	v_mov_b32_e32 v32, v225
	s_mov_b32 vcc_lo, s91
	v_mov_b64_e32 v[118:119], v[78:79]
	v_mov_b64_e32 v[126:127], v[82:83]
	s_branch .LBB0_1549
